# plus: accumulator zeroing with 64-bit moves
# baseline (speedup 1.0000x reference)
; template <class Epi, class Sched, bool ALIGN_EPI = false, bool SP2 = false>
; __device__ __forceinline__ void gemm_phase(LAS unsigned char* lds, const Gemm g, const Sched& S, const Epi& E, const int tid_) {
;     ...
;         const bool has_next = S.next(ui + 1, nxt);
;         const char* nA = has_next ? (const char*)g.A + (size_t)nxt.pm * tstep : cA; const char* nB = has_next ? (const char*)g.Bt + (size_t)nxt.pn * tstep : cB;
;         for (int t = 0; t < nt; t += 2) {
;             const bool last = (t == nt - 2);
;             const char* a1 = cA + (size_t)(t + 1) * kstep;
;             const char* a2 = last ? nA : cA + (size_t)(t + 2) * kstep; const char* b2 = last ? nB : cB + (size_t)(t + 2) * kstep;
;             const char* a3 = a2 + kstep; const char* b3 = b2 + kstep;
;             if (last && has_next) S.a_ready(nxt);
;     ...
; #pragma unroll
;         for (int a = 0; a < 2; ++a)
; #pragma unroll
;             for (int b = 0; b < 2; ++b)
; #pragma unroll
;                 for (int m = 0; m < 4; ++m)
; #pragma unroll
;                     for (int n = 0; n < 2; ++n) acc[a][b][m][n] = (f32x4){0.f, 0.f, 0.f, 0.f};
;         cur = nxt; cA = nA; cB = nB; ++ui;
.LBB0_33:
	s_ashr_i32 s17, s16, 31
	s_lshl_b64 s[18:19], s[16:17], 20
	s_add_u32 s18, s29, s18
	s_addc_u32 s19, s30, s19
	s_and_b64 s[42:43], s[40:41], exec
	s_cselect_b32 s17, s19, s47
	s_cselect_b32 s21, s18, s46
	s_ashr_i32 s15, s14, 31
	s_lshl_b64 s[42:43], s[14:15], 20
	s_add_u32 s42, s31, s42
	s_addc_u32 s43, s54, s43
	s_and_b64 s[50:51], s[40:41], exec
	s_cselect_b32 s15, s43, s49
	s_cselect_b32 s64, s42, s48
	s_add_u32 s46, s46, 0x80080
	s_addc_u32 s47, s47, 0
	s_add_u32 s65, s48, 0x100
	v_mov_b32_e32 v2, 0
	s_addc_u32 s66, s49, 0
	s_mov_b32 s67, -2
	v_mov_b32_e32 v3, v2
	v_mov_b64_e32 v[4:5], 0
	v_mov_b64_e32 v[6:7], 0
	v_mov_b64_e32 v[8:9], 0
	v_mov_b64_e32 v[10:11], 0
	v_mov_b64_e32 v[12:13], 0
	v_mov_b64_e32 v[14:15], 0
	v_mov_b64_e32 v[16:17], 0
	v_mov_b64_e32 v[18:19], 0
	v_mov_b64_e32 v[20:21], 0
	v_mov_b64_e32 v[22:23], 0
	v_mov_b64_e32 v[24:25], 0
	v_mov_b64_e32 v[26:27], 0
	v_mov_b64_e32 v[28:29], 0
	v_mov_b64_e32 v[30:31], 0
	v_mov_b64_e32 v[32:33], 0
	v_mov_b64_e32 v[34:35], 0
	v_mov_b64_e32 v[36:37], 0
	v_mov_b64_e32 v[38:39], 0
	v_mov_b64_e32 v[40:41], 0
	v_mov_b64_e32 v[42:43], 0
	v_mov_b64_e32 v[44:45], 0
	v_mov_b64_e32 v[46:47], 0
	v_mov_b64_e32 v[48:49], 0
	v_mov_b64_e32 v[50:51], 0
	v_mov_b64_e32 v[52:53], 0
	v_mov_b64_e32 v[54:55], 0
	v_mov_b64_e32 v[56:57], 0
	v_mov_b64_e32 v[58:59], 0
	v_mov_b64_e32 v[60:61], 0
	v_mov_b64_e32 v[62:63], 0
	v_mov_b64_e32 v[64:65], 0
	v_mov_b64_e32 v[66:67], 0
	v_mov_b64_e32 v[68:69], 0
	v_mov_b64_e32 v[70:71], 0
	v_mov_b64_e32 v[72:73], 0
	v_mov_b64_e32 v[74:75], 0
	v_mov_b64_e32 v[76:77], 0
	v_mov_b64_e32 v[78:79], 0
	v_mov_b64_e32 v[80:81], 0
	v_mov_b64_e32 v[82:83], 0
	v_mov_b64_e32 v[84:85], 0
	v_mov_b64_e32 v[86:87], 0
	v_mov_b64_e32 v[88:89], 0
	v_mov_b64_e32 v[90:91], 0
	v_mov_b64_e32 v[92:93], 0
	v_mov_b64_e32 v[94:95], 0
	v_mov_b64_e32 v[96:97], 0
	v_mov_b64_e32 v[98:99], 0
	v_mov_b64_e32 v[100:101], 0
	v_mov_b64_e32 v[102:103], 0
	v_mov_b64_e32 v[104:105], 0
	v_mov_b64_e32 v[106:107], 0
	v_mov_b64_e32 v[108:109], 0
	v_mov_b64_e32 v[110:111], 0
	v_mov_b64_e32 v[112:113], 0
	v_mov_b64_e32 v[114:115], 0
	v_mov_b64_e32 v[116:117], 0
	v_mov_b64_e32 v[118:119], 0
	v_mov_b64_e32 v[120:121], 0
	v_mov_b64_e32 v[122:123], 0
	v_mov_b64_e32 v[124:125], 0
	v_mov_b64_e32 v[126:127], 0
	v_mov_b64_e32 v[128:129], 0

; template <class Epi, class Sched, bool ALIGN_EPI = false, bool SP2 = false>
; __device__ __forceinline__ void gemm_phase(LAS unsigned char* lds, const Gemm g, const Sched& S, const Epi& E, const int tid_) {
;     ...
;         const bool has_next = S.next(ui + 1, nxt);
;         const char* nA = has_next ? (const char*)g.A + (size_t)nxt.pm * tstep : cA; const char* nB = has_next ? (const char*)g.Bt + (size_t)nxt.pn * tstep : cB;
;         for (int t = 0; t < nt; t += 2) {
;             const bool last = (t == nt - 2);
;             const char* a1 = cA + (size_t)(t + 1) * kstep;
;             const char* a2 = last ? nA : cA + (size_t)(t + 2) * kstep; const char* b2 = last ? nB : cB + (size_t)(t + 2) * kstep;
;             const char* a3 = a2 + kstep; const char* b3 = b2 + kstep;
;             if (last && has_next) S.a_ready(nxt);
;     ...
; #pragma unroll
;         for (int a = 0; a < 2; ++a)
; #pragma unroll
;             for (int b = 0; b < 2; ++b)
; #pragma unroll
;                 for (int m = 0; m < 4; ++m)
; #pragma unroll
;                     for (int n = 0; n < 2; ++n) acc[a][b][m][n] = (f32x4){0.f, 0.f, 0.f, 0.f};
;         cur = nxt; cA = nA; cB = nB; ++ui;
.LBB0_69:
	s_ashr_i32 s17, s16, 31
	s_lshl_b64 s[18:19], s[16:17], 20
	s_add_u32 s18, s29, s18
	s_addc_u32 s19, s30, s19
	s_and_b64 s[42:43], s[40:41], exec
	s_cselect_b32 s17, s19, s47
	s_cselect_b32 s21, s18, s46
	s_ashr_i32 s15, s14, 31
	s_lshl_b64 s[42:43], s[14:15], 20
	s_add_u32 s42, s31, s42
	s_addc_u32 s43, s56, s43
	s_and_b64 s[50:51], s[40:41], exec
	s_cselect_b32 s15, s43, s49
	s_cselect_b32 s66, s42, s48
	s_add_u32 s67, s48, 0x100
	v_mov_b32_e32 v2, 0
	s_addc_u32 s68, s49, 0
	s_mov_b32 s69, -2
	v_mov_b32_e32 v3, v2
	v_mov_b64_e32 v[4:5], 0
	v_mov_b64_e32 v[6:7], 0
	v_mov_b64_e32 v[8:9], 0
	v_mov_b64_e32 v[10:11], 0
	v_mov_b64_e32 v[12:13], 0
	v_mov_b64_e32 v[14:15], 0
	v_mov_b64_e32 v[16:17], 0
	v_mov_b64_e32 v[18:19], 0
	v_mov_b64_e32 v[20:21], 0
	v_mov_b64_e32 v[22:23], 0
	v_mov_b64_e32 v[24:25], 0
	v_mov_b64_e32 v[26:27], 0
	v_mov_b64_e32 v[28:29], 0
	v_mov_b64_e32 v[30:31], 0
	v_mov_b64_e32 v[32:33], 0
	v_mov_b64_e32 v[34:35], 0
	v_mov_b64_e32 v[36:37], 0
	v_mov_b64_e32 v[38:39], 0
	v_mov_b64_e32 v[40:41], 0
	v_mov_b64_e32 v[42:43], 0
	v_mov_b64_e32 v[44:45], 0
	v_mov_b64_e32 v[46:47], 0
	v_mov_b64_e32 v[48:49], 0
	v_mov_b64_e32 v[50:51], 0
	v_mov_b64_e32 v[52:53], 0
	v_mov_b64_e32 v[54:55], 0
	v_mov_b64_e32 v[56:57], 0
	v_mov_b64_e32 v[58:59], 0
	v_mov_b64_e32 v[60:61], 0
	v_mov_b64_e32 v[62:63], 0
	v_mov_b64_e32 v[64:65], 0
	v_mov_b64_e32 v[66:67], 0
	v_mov_b64_e32 v[68:69], 0
	v_mov_b64_e32 v[70:71], 0
	v_mov_b64_e32 v[72:73], 0
	v_mov_b64_e32 v[74:75], 0
	v_mov_b64_e32 v[76:77], 0
	v_mov_b64_e32 v[78:79], 0
	v_mov_b64_e32 v[80:81], 0
	v_mov_b64_e32 v[82:83], 0
	v_mov_b64_e32 v[84:85], 0
	v_mov_b64_e32 v[86:87], 0
	v_mov_b64_e32 v[88:89], 0
	v_mov_b64_e32 v[90:91], 0
	v_mov_b64_e32 v[92:93], 0
	v_mov_b64_e32 v[94:95], 0
	v_mov_b64_e32 v[96:97], 0
	v_mov_b64_e32 v[98:99], 0
	v_mov_b64_e32 v[100:101], 0
	v_mov_b64_e32 v[102:103], 0
	v_mov_b64_e32 v[104:105], 0
	v_mov_b64_e32 v[106:107], 0
	v_mov_b64_e32 v[108:109], 0
	v_mov_b64_e32 v[110:111], 0
	v_mov_b64_e32 v[112:113], 0
	v_mov_b64_e32 v[114:115], 0
	v_mov_b64_e32 v[116:117], 0
	v_mov_b64_e32 v[118:119], 0
	v_mov_b64_e32 v[120:121], 0
	v_mov_b64_e32 v[122:123], 0
	v_mov_b64_e32 v[124:125], 0
	v_mov_b64_e32 v[126:127], 0
	v_mov_b64_e32 v[128:129], 0

; template <class Epi, class Sched, bool ALIGN_EPI = false, bool SP2 = false>
; __device__ __forceinline__ void gemm_phase(LAS unsigned char* lds, const Gemm g, const Sched& S, const Epi& E, const int tid_) {
;     ...
;         const bool has_next = S.next(ui + 1, nxt);
;         const char* nA = has_next ? (const char*)g.A + (size_t)nxt.pm * tstep : cA; const char* nB = has_next ? (const char*)g.Bt + (size_t)nxt.pn * tstep : cB;
;         for (int t = 0; t < nt; t += 2) {
;             const bool last = (t == nt - 2);
;             const char* a1 = cA + (size_t)(t + 1) * kstep;
;             const char* a2 = last ? nA : cA + (size_t)(t + 2) * kstep; const char* b2 = last ? nB : cB + (size_t)(t + 2) * kstep;
;             const char* a3 = a2 + kstep; const char* b3 = b2 + kstep;
;             if (last && has_next) S.a_ready(nxt);
;     ...
; #pragma unroll
;         for (int a = 0; a < 2; ++a)
; #pragma unroll
;             for (int b = 0; b < 2; ++b)
; #pragma unroll
;                 for (int m = 0; m < 4; ++m)
; #pragma unroll
;                     for (int n = 0; n < 2; ++n) acc[a][b][m][n] = (f32x4){0.f, 0.f, 0.f, 0.f};
;         cur = nxt; cA = nA; cB = nB; ++ui;
.LBB0_95:
	s_ashr_i32 s19, s18, 31
	s_lshl_b64 s[20:21], s[18:19], 19
	s_add_u32 s44, s30, s20
	s_addc_u32 s45, s31, s21
	s_and_b64 s[20:21], s[40:41], exec
	s_cselect_b32 s19, s45, s51
	s_cselect_b32 s20, s44, s50
	s_ashr_i32 s17, s16, 31
	s_lshl_b64 s[46:47], s[16:17], 19
	s_add_u32 s46, s58, s46
	s_addc_u32 s47, s59, s47
	s_and_b64 s[56:57], s[40:41], exec
	s_cselect_b32 s17, s47, s55
	s_cselect_b32 s21, s46, s54
	s_add_u32 s50, s50, 0x40080
	s_addc_u32 s51, s51, 0
	s_add_u32 s69, s54, 0x100
	v_mov_b32_e32 v2, 0
	s_addc_u32 s70, s55, 0
	s_mov_b32 s71, -2
	v_mov_b32_e32 v3, v2
	v_mov_b64_e32 v[4:5], 0
	v_mov_b64_e32 v[6:7], 0
	v_mov_b64_e32 v[8:9], 0
	v_mov_b64_e32 v[10:11], 0
	v_mov_b64_e32 v[12:13], 0
	v_mov_b64_e32 v[14:15], 0
	v_mov_b64_e32 v[16:17], 0
	v_mov_b64_e32 v[18:19], 0
	v_mov_b64_e32 v[20:21], 0
	v_mov_b64_e32 v[22:23], 0
	v_mov_b64_e32 v[24:25], 0
	v_mov_b64_e32 v[26:27], 0
	v_mov_b64_e32 v[28:29], 0
	v_mov_b64_e32 v[30:31], 0
	v_mov_b64_e32 v[32:33], 0
	v_mov_b64_e32 v[34:35], 0
	v_mov_b64_e32 v[36:37], 0
	v_mov_b64_e32 v[38:39], 0
	v_mov_b64_e32 v[40:41], 0
	v_mov_b64_e32 v[42:43], 0
	v_mov_b64_e32 v[44:45], 0
	v_mov_b64_e32 v[46:47], 0
	v_mov_b64_e32 v[48:49], 0
	v_mov_b64_e32 v[50:51], 0
	v_mov_b64_e32 v[52:53], 0
	v_mov_b64_e32 v[54:55], 0
	v_mov_b64_e32 v[56:57], 0
	v_mov_b64_e32 v[58:59], 0
	v_mov_b64_e32 v[60:61], 0
	v_mov_b64_e32 v[62:63], 0
	v_mov_b64_e32 v[64:65], 0
	v_mov_b64_e32 v[66:67], 0
	v_mov_b64_e32 v[68:69], 0
	v_mov_b64_e32 v[70:71], 0
	v_mov_b64_e32 v[72:73], 0
	v_mov_b64_e32 v[74:75], 0
	v_mov_b64_e32 v[76:77], 0
	v_mov_b64_e32 v[78:79], 0
	v_mov_b64_e32 v[80:81], 0
	v_mov_b64_e32 v[82:83], 0
	v_mov_b64_e32 v[84:85], 0
	v_mov_b64_e32 v[86:87], 0
	v_mov_b64_e32 v[88:89], 0
	v_mov_b64_e32 v[90:91], 0
	v_mov_b64_e32 v[92:93], 0
	v_mov_b64_e32 v[94:95], 0
	v_mov_b64_e32 v[96:97], 0
	v_mov_b64_e32 v[98:99], 0
	v_mov_b64_e32 v[100:101], 0
	v_mov_b64_e32 v[102:103], 0
	v_mov_b64_e32 v[104:105], 0
	v_mov_b64_e32 v[106:107], 0
	v_mov_b64_e32 v[108:109], 0
	v_mov_b64_e32 v[110:111], 0
	v_mov_b64_e32 v[112:113], 0
	v_mov_b64_e32 v[114:115], 0
	v_mov_b64_e32 v[116:117], 0
	v_mov_b64_e32 v[118:119], 0
	v_mov_b64_e32 v[120:121], 0
	v_mov_b64_e32 v[122:123], 0
	v_mov_b64_e32 v[124:125], 0
	v_mov_b64_e32 v[126:127], 0
	v_mov_b64_e32 v[128:129], 0

; template <class Epi, class Sched, bool ALIGN_EPI = false, bool SP2 = false>
; __device__ __forceinline__ void gemm_phase(LAS unsigned char* lds, const Gemm g, const Sched& S, const Epi& E, const int tid_) {
;     ...
;         const bool has_next = S.next(ui + 1, nxt);
;         const char* nA = has_next ? (const char*)g.A + (size_t)nxt.pm * tstep : cA; const char* nB = has_next ? (const char*)g.Bt + (size_t)nxt.pn * tstep : cB;
;         for (int t = 0; t < nt; t += 2) {
;             const bool last = (t == nt - 2);
;             const char* a1 = cA + (size_t)(t + 1) * kstep;
;             const char* a2 = last ? nA : cA + (size_t)(t + 2) * kstep; const char* b2 = last ? nB : cB + (size_t)(t + 2) * kstep;
;             const char* a3 = a2 + kstep; const char* b3 = b2 + kstep;
;             if (last && has_next) S.a_ready(nxt);
;     ...
; #pragma unroll
;         for (int a = 0; a < 2; ++a)
; #pragma unroll
;             for (int b = 0; b < 2; ++b)
; #pragma unroll
;                 for (int m = 0; m < 4; ++m)
; #pragma unroll
;                     for (int n = 0; n < 2; ++n) acc[a][b][m][n] = (f32x4){0.f, 0.f, 0.f, 0.f};
;         cur = nxt; cA = nA; cB = nB; ++ui;
.LBB0_119:
	s_ashr_i32 s17, s16, 31
	s_lshl_b64 s[18:19], s[16:17], 19
	s_add_u32 s18, s30, s18
	s_addc_u32 s19, s31, s19
	s_and_b64 s[44:45], s[40:41], exec
	s_cselect_b32 s17, s19, s49
	s_cselect_b32 s21, s18, s48
	s_ashr_i32 s15, s14, 31
	s_lshl_b64 s[44:45], s[14:15], 19
	s_add_u32 s44, s56, s44
	s_addc_u32 s45, s57, s45
	s_and_b64 s[54:55], s[40:41], exec
	s_cselect_b32 s15, s45, s51
	s_cselect_b32 s66, s44, s50
	s_add_u32 s48, s48, 0x40080
	s_addc_u32 s49, s49, 0
	s_add_u32 s67, s50, 0x100
	v_mov_b32_e32 v2, 0
	s_addc_u32 s68, s51, 0
	s_mov_b32 s69, -2
	v_mov_b32_e32 v3, v2
	v_mov_b64_e32 v[4:5], 0
	v_mov_b64_e32 v[6:7], 0
	v_mov_b64_e32 v[8:9], 0
	v_mov_b64_e32 v[10:11], 0
	v_mov_b64_e32 v[12:13], 0
	v_mov_b64_e32 v[14:15], 0
	v_mov_b64_e32 v[16:17], 0
	v_mov_b64_e32 v[18:19], 0
	v_mov_b64_e32 v[20:21], 0
	v_mov_b64_e32 v[22:23], 0
	v_mov_b64_e32 v[24:25], 0
	v_mov_b64_e32 v[26:27], 0
	v_mov_b64_e32 v[28:29], 0
	v_mov_b64_e32 v[30:31], 0
	v_mov_b64_e32 v[32:33], 0
	v_mov_b64_e32 v[34:35], 0
	v_mov_b64_e32 v[36:37], 0
	v_mov_b64_e32 v[38:39], 0
	v_mov_b64_e32 v[40:41], 0
	v_mov_b64_e32 v[42:43], 0
	v_mov_b64_e32 v[44:45], 0
	v_mov_b64_e32 v[46:47], 0
	v_mov_b64_e32 v[48:49], 0
	v_mov_b64_e32 v[50:51], 0
	v_mov_b64_e32 v[52:53], 0
	v_mov_b64_e32 v[54:55], 0
	v_mov_b64_e32 v[56:57], 0
	v_mov_b64_e32 v[58:59], 0
	v_mov_b64_e32 v[60:61], 0
	v_mov_b64_e32 v[62:63], 0
	v_mov_b64_e32 v[64:65], 0
	v_mov_b64_e32 v[66:67], 0
	v_mov_b64_e32 v[68:69], 0
	v_mov_b64_e32 v[70:71], 0
	v_mov_b64_e32 v[72:73], 0
	v_mov_b64_e32 v[74:75], 0
	v_mov_b64_e32 v[76:77], 0
	v_mov_b64_e32 v[78:79], 0
	v_mov_b64_e32 v[80:81], 0
	v_mov_b64_e32 v[82:83], 0
	v_mov_b64_e32 v[84:85], 0
	v_mov_b64_e32 v[86:87], 0
	v_mov_b64_e32 v[88:89], 0
	v_mov_b64_e32 v[90:91], 0
	v_mov_b64_e32 v[92:93], 0
	v_mov_b64_e32 v[94:95], 0
	v_mov_b64_e32 v[96:97], 0
	v_mov_b64_e32 v[98:99], 0
	v_mov_b64_e32 v[100:101], 0
	v_mov_b64_e32 v[102:103], 0
	v_mov_b64_e32 v[104:105], 0
	v_mov_b64_e32 v[106:107], 0
	v_mov_b64_e32 v[108:109], 0
	v_mov_b64_e32 v[110:111], 0
	v_mov_b64_e32 v[112:113], 0
	v_mov_b64_e32 v[114:115], 0
	v_mov_b64_e32 v[116:117], 0
	v_mov_b64_e32 v[118:119], 0
	v_mov_b64_e32 v[120:121], 0
	v_mov_b64_e32 v[122:123], 0
	v_mov_b64_e32 v[124:125], 0
	v_mov_b64_e32 v[126:127], 0
	v_mov_b64_e32 v[128:129], 0

; template <class Epi, class Sched, bool ALIGN_EPI = false, bool SP2 = false>
; __device__ __forceinline__ void gemm_phase(LAS unsigned char* lds, const Gemm g, const Sched& S, const Epi& E, const int tid_) {
;     ...
;         const bool has_next = S.next(ui + 1, nxt);
;         const char* nA = has_next ? (const char*)g.A + (size_t)nxt.pm * tstep : cA; const char* nB = has_next ? (const char*)g.Bt + (size_t)nxt.pn * tstep : cB;
;         for (int t = 0; t < nt; t += 2) {
;             const bool last = (t == nt - 2);
;             const char* a1 = cA + (size_t)(t + 1) * kstep;
;             const char* a2 = last ? nA : cA + (size_t)(t + 2) * kstep; const char* b2 = last ? nB : cB + (size_t)(t + 2) * kstep;
;             const char* a3 = a2 + kstep; const char* b3 = b2 + kstep;
;             if (last && has_next) S.a_ready(nxt);
;     ...
; #pragma unroll
;         for (int a = 0; a < 2; ++a)
; #pragma unroll
;             for (int b = 0; b < 2; ++b)
; #pragma unroll
;                 for (int m = 0; m < 4; ++m)
; #pragma unroll
;                     for (int n = 0; n < 2; ++n) acc[a][b][m][n] = (f32x4){0.f, 0.f, 0.f, 0.f};
;         cur = nxt; cA = nA; cB = nB; ++ui;
.LBB0_252:
	s_ashr_i32 s49, s48, 31
	s_lshl_b64 s[20:21], s[48:49], 20
	s_add_u32 s50, s7, s20
	s_addc_u32 s51, s29, s21
	s_and_b64 s[20:21], s[40:41], exec
	s_cselect_b32 s20, s51, s55
	s_cselect_b32 s21, s50, s54
	s_ashr_i32 s47, s46, 31
	s_lshl_b64 s[52:53], s[46:47], 20
	s_add_u32 s52, s30, s52
	s_addc_u32 s53, s31, s53
	s_and_b64 s[60:61], s[40:41], exec
	s_cselect_b32 s43, s53, s59
	s_cselect_b32 s47, s52, s58
	s_add_u32 s54, s54, 0x80080
	s_addc_u32 s55, s55, 0
	s_add_u32 s49, s58, 0x100
	v_mov_b32_e32 v2, 0
	s_addc_u32 s72, s59, 0
	s_mov_b32 s73, -2
	v_mov_b32_e32 v3, v2
	v_mov_b64_e32 v[4:5], 0
	v_mov_b64_e32 v[6:7], 0
	v_mov_b64_e32 v[8:9], 0
	v_mov_b64_e32 v[10:11], 0
	v_mov_b64_e32 v[12:13], 0
	v_mov_b64_e32 v[14:15], 0
	v_mov_b64_e32 v[16:17], 0
	v_mov_b64_e32 v[18:19], 0
	v_mov_b64_e32 v[20:21], 0
	v_mov_b64_e32 v[22:23], 0
	v_mov_b64_e32 v[24:25], 0
	v_mov_b64_e32 v[26:27], 0
	v_mov_b64_e32 v[28:29], 0
	v_mov_b64_e32 v[30:31], 0
	v_mov_b64_e32 v[32:33], 0
	v_mov_b64_e32 v[34:35], 0
	v_mov_b64_e32 v[36:37], 0
	v_mov_b64_e32 v[38:39], 0
	v_mov_b64_e32 v[40:41], 0
	v_mov_b64_e32 v[42:43], 0
	v_mov_b64_e32 v[44:45], 0
	v_mov_b64_e32 v[46:47], 0
	v_mov_b64_e32 v[48:49], 0
	v_mov_b64_e32 v[50:51], 0
	v_mov_b64_e32 v[52:53], 0
	v_mov_b64_e32 v[54:55], 0
	v_mov_b64_e32 v[56:57], 0
	v_mov_b64_e32 v[58:59], 0
	v_mov_b64_e32 v[60:61], 0
	v_mov_b64_e32 v[62:63], 0
	v_mov_b64_e32 v[64:65], 0
	v_mov_b64_e32 v[66:67], 0
	v_mov_b64_e32 v[68:69], 0
	v_mov_b64_e32 v[70:71], 0
	v_mov_b64_e32 v[72:73], 0
	v_mov_b64_e32 v[74:75], 0
	v_mov_b64_e32 v[76:77], 0
	v_mov_b64_e32 v[78:79], 0
	v_mov_b64_e32 v[80:81], 0
	v_mov_b64_e32 v[82:83], 0
	v_mov_b64_e32 v[84:85], 0
	v_mov_b64_e32 v[86:87], 0
	v_mov_b64_e32 v[88:89], 0
	v_mov_b64_e32 v[90:91], 0
	v_mov_b64_e32 v[92:93], 0
	v_mov_b64_e32 v[94:95], 0
	v_mov_b64_e32 v[96:97], 0
	v_mov_b64_e32 v[98:99], 0
	v_mov_b64_e32 v[100:101], 0
	v_mov_b64_e32 v[102:103], 0
	v_mov_b64_e32 v[104:105], 0
	v_mov_b64_e32 v[106:107], 0
	v_mov_b64_e32 v[108:109], 0
	v_mov_b64_e32 v[110:111], 0
	v_mov_b64_e32 v[112:113], 0
	v_mov_b64_e32 v[114:115], 0
	v_mov_b64_e32 v[116:117], 0
	v_mov_b64_e32 v[118:119], 0
	v_mov_b64_e32 v[120:121], 0
	v_mov_b64_e32 v[122:123], 0
	v_mov_b64_e32 v[124:125], 0
	v_mov_b64_e32 v[126:127], 0
	v_mov_b64_e32 v[128:129], 0

; template <class Epi, class Sched, bool ALIGN_EPI = false, bool SP2 = false>
; __device__ __forceinline__ void gemm_phase(LAS unsigned char* lds, const Gemm g, const Sched& S, const Epi& E, const int tid_) {
;     ...
;         const bool has_next = S.next(ui + 1, nxt);
;         const char* nA = has_next ? (const char*)g.A + (size_t)nxt.pm * tstep : cA; const char* nB = has_next ? (const char*)g.Bt + (size_t)nxt.pn * tstep : cB;
;         for (int t = 0; t < nt; t += 2) {
;             const bool last = (t == nt - 2);
;             const char* a1 = cA + (size_t)(t + 1) * kstep;
;             const char* a2 = last ? nA : cA + (size_t)(t + 2) * kstep; const char* b2 = last ? nB : cB + (size_t)(t + 2) * kstep;
;             const char* a3 = a2 + kstep; const char* b3 = b2 + kstep;
;             if (last && has_next) S.a_ready(nxt);
;     ...
; #pragma unroll
;         for (int a = 0; a < 2; ++a)
; #pragma unroll
;             for (int b = 0; b < 2; ++b)
; #pragma unroll
;                 for (int m = 0; m < 4; ++m)
; #pragma unroll
;                     for (int n = 0; n < 2; ++n) acc[a][b][m][n] = (f32x4){0.f, 0.f, 0.f, 0.f};
;         cur = nxt; cA = nA; cB = nB; ++ui;
.LBB0_358:
	s_ashr_i32 s17, s16, 31
	s_lshl_b64 s[18:19], s[16:17], 22
	s_add_u32 s18, s29, s18
	s_addc_u32 s19, s30, s19
	s_and_b64 s[42:43], s[40:41], exec
	s_cselect_b32 s17, s19, s47
	s_cselect_b32 s21, s18, s46
	s_ashr_i32 s15, s14, 31
	s_lshl_b64 s[42:43], s[14:15], 22
	s_add_u32 s42, s31, s42
	s_addc_u32 s43, s54, s43
	s_and_b64 s[50:51], s[40:41], exec
	s_cselect_b32 s15, s43, s49
	s_cselect_b32 s64, s42, s48
	s_add_u32 s65, s48, 0x100
	v_mov_b32_e32 v2, 0
	s_addc_u32 s66, s49, 0
	s_mov_b32 s67, -2
	v_mov_b32_e32 v3, v2
	v_mov_b64_e32 v[4:5], 0
	v_mov_b64_e32 v[6:7], 0
	v_mov_b64_e32 v[8:9], 0
	v_mov_b64_e32 v[10:11], 0
	v_mov_b64_e32 v[12:13], 0
	v_mov_b64_e32 v[14:15], 0
	v_mov_b64_e32 v[16:17], 0
	v_mov_b64_e32 v[18:19], 0
	v_mov_b64_e32 v[20:21], 0
	v_mov_b64_e32 v[22:23], 0
	v_mov_b64_e32 v[24:25], 0
	v_mov_b64_e32 v[26:27], 0
	v_mov_b64_e32 v[28:29], 0
	v_mov_b64_e32 v[30:31], 0
	v_mov_b64_e32 v[32:33], 0
	v_mov_b64_e32 v[34:35], 0
	v_mov_b64_e32 v[36:37], 0
	v_mov_b64_e32 v[38:39], 0
	v_mov_b64_e32 v[40:41], 0
	v_mov_b64_e32 v[42:43], 0
	v_mov_b64_e32 v[44:45], 0
	v_mov_b64_e32 v[46:47], 0
	v_mov_b64_e32 v[48:49], 0
	v_mov_b64_e32 v[50:51], 0
	v_mov_b64_e32 v[52:53], 0
	v_mov_b64_e32 v[54:55], 0
	v_mov_b64_e32 v[56:57], 0
	v_mov_b64_e32 v[58:59], 0
	v_mov_b64_e32 v[60:61], 0
	v_mov_b64_e32 v[62:63], 0
	v_mov_b64_e32 v[64:65], 0
	v_mov_b64_e32 v[66:67], 0
	v_mov_b64_e32 v[68:69], 0
	v_mov_b64_e32 v[70:71], 0
	v_mov_b64_e32 v[72:73], 0
	v_mov_b64_e32 v[74:75], 0
	v_mov_b64_e32 v[76:77], 0
	v_mov_b64_e32 v[78:79], 0
	v_mov_b64_e32 v[80:81], 0
	v_mov_b64_e32 v[82:83], 0
	v_mov_b64_e32 v[84:85], 0
	v_mov_b64_e32 v[86:87], 0
	v_mov_b64_e32 v[88:89], 0
	v_mov_b64_e32 v[90:91], 0
	v_mov_b64_e32 v[92:93], 0
	v_mov_b64_e32 v[94:95], 0
	v_mov_b64_e32 v[96:97], 0
	v_mov_b64_e32 v[98:99], 0
	v_mov_b64_e32 v[100:101], 0
	v_mov_b64_e32 v[102:103], 0
	v_mov_b64_e32 v[104:105], 0
	v_mov_b64_e32 v[106:107], 0
	v_mov_b64_e32 v[108:109], 0
	v_mov_b64_e32 v[110:111], 0
	v_mov_b64_e32 v[112:113], 0
	v_mov_b64_e32 v[114:115], 0
	v_mov_b64_e32 v[116:117], 0
	v_mov_b64_e32 v[118:119], 0
	v_mov_b64_e32 v[120:121], 0
	v_mov_b64_e32 v[122:123], 0
	v_mov_b64_e32 v[124:125], 0
	v_mov_b64_e32 v[126:127], 0
	v_mov_b64_e32 v[128:129], 0
